# S5 output stage stagger: waves 4-7 delayed by s_sleep 48
# baseline (speedup 1.0000x reference)
; #define LAS __attribute__((address_space(3)))
; #define S5_LAUNDER() int tid_ = tid0, lane_ = lane0; asm volatile("" : "+v"(tid_), "+v"(lane_)); const int tid = tid_, lane = lane_, fr = lane & 15, fq = lane >> 4; (void)tid; (void)fr; (void)fq
; __device__ __forceinline__ void s5_prompt_item_mfma(LAS unsigned char* lds, int tid0, int lane0, int wave, int n, int g, const bf16* USg, const bf16* FTg, const bf16* WTg, const bf16* GTg, ...
;     ...
;     S5_LAUNDER();
; #pragma unroll
;     for (int it = 0; it < 4; ++it) { const int q = tid + 512 * it; *(LAS v4u*)(lds + R2_OFF + q * 16) = ftq[it]; }
;     const f32x4 dk = *(const f32x4*)(dsk + 4 * fq);
;     __syncthreads();
;     bf16x8 hbv[4][4];
; #pragma unroll
;     for (int kk = 0; kk < 4; ++kk)
; #pragma unroll
;         for (int cb = 0; cb < 4; ++cb) hbv[kk][cb] = *(const LAS bf16x8*)(lds + HP_OFF + (16 * cb + fr) * 272 + 64 * kk + 16 * fq);
.LBB0_852:
	s_or_b64 exec, exec, s[54:55]
	v_mov_b32_e32 v201, v196
	v_mov_b32_e32 v2, v192
	s_lshl_b32 s10, s65, 6
	s_barrier
	s_add_u32 s10, s52, s10
	v_ashrrev_i32_e32 v202, 4, v201
	v_lshlrev_b32_e32 v194, 2, v202
	s_addc_u32 s11, s53, 0
	v_ashrrev_i32_e32 v195, 31, v194
	v_lshl_add_u64 v[20:21], v[194:195], 2, s[10:11]
	global_load_dwordx4 v[20:23], v[20:21], off
	s_add_i32 s10, 0, 0x10800
	v_and_b32_e32 v203, 15, v201
	v_lshl_add_u32 v2, v2, 4, s10
	s_waitcnt vmcnt(20)
	ds_write_b128 v2, v[24:27]
	s_waitcnt vmcnt(19)
	ds_write_b128 v2, v[28:31] offset:8192
	s_waitcnt vmcnt(18)
	ds_write_b128 v2, v[32:35] offset:16384
	s_waitcnt vmcnt(17)
	ds_write_b128 v2, v[36:39] offset:24576
	v_and_b32_e32 v2, -16, v201
	s_add_i32 s11, 0, 0x18c00
	v_mul_u32_u24_e32 v24, 0x110, v203
	v_add3_u32 v2, s11, v2, v24
	s_waitcnt lgkmcnt(0)
	s_barrier
	v_readfirstlane_b32 s99, v192
	s_nop 3
	s_lshr_b32 s99, s99, 6
	s_cmp_lt_u32 s99, 4
	s_cbranch_scc1 .Ls5_stag
	s_sleep 48
